# scan / A pass 2 order swap now keyed on (wave >= 4) xor (blockIdx bit 3)
# baseline (speedup 1.0000x reference)
; #define LAS __attribute__((address_space(3)))
; #define LAUNDER() int tp = TID0(); const int tid = tp, lane = tp & 63, wave = __builtin_amdgcn_readfirstlane(tp >> 6); (void)tid; (void)lane; (void)wave
; __global__ void __launch_bounds__(512) fwd_kernel(Args a) {
;     ...
;         if (IN(pb + 3) && EN_SCAN) { LAUNDER(); ssd_scan(STATES, TOT, blockIdx.x * 512 + tid, G * 512); }
;         if (IN(pb + 3) && EN_A) { LAUNDER(); LAS char* vt = (LAS char*)lds + wave * 16384;
;             for (int u = blockIdx.x; u < 512; u += G) { mixerA2_unit(u, PROJ, YC, LPA, KMAX + l * 1024, vt, wave, lane); } }
.Lsw_scan:
	s_cmp_eq_u32 s100, 0
	s_cbranch_scc0 .Lsw_doscan
	v_readlane_b32 s0, v253, 0
	s_nop 0
	s_lshr_b32 s0, s0, 8
	s_lshr_b32 s1, s66, 3
	s_xor_b32 s0, s0, s1
	s_bitcmp1_b32 s0, 0
	s_cbranch_scc0 .Lsw_doscan
	s_mov_b32 s100, 1
	s_branch .Lsw_a2
